# P8 epilogue store addressing: stores 1-3 / 5-7 reuse the address of store 0 / 4 with immediate offsets (12 64-bit address ops removed per wave per tile); on top of p1pk + p8pk + czero
# baseline (speedup 1.0000x reference)
; __device__ __forceinline__ u32x4 pack8(const f32x4 a, const f32x4 b) { u32x4 w; w.x = cvt_pk_bf16(a[0], a[1]); w.y = cvt_pk_bf16(a[2], a[3]); w.z = cvt_pk_bf16(b[0], b[1]); w.w = cvt_pk_bf16(b[2], b[3]); return w; }
; #define EPI_ROWLOOP _Pragma("unroll") for (int ai = 0; ai < 2; ++ai) _Pragma("unroll") for (int m = 0; m < 4; ++m)
; __device__ __forceinline__ float sigm(float x) { return __builtin_amdgcn_rcpf(1.0f + __builtin_amdgcn_exp2f(x * -1.4426950408889634f)); }
; __device__ __forceinline__ float sigm_new(float x) { return __builtin_amdgcn_rcpf(1.0f + __builtin_amdgcn_exp2f(x * -1.4426950408889634f)); }
; __device__ __forceinline__ f32x4 sigm4_new(const f32x4 v) { f32x4 o; o[0] = sigm_new(v[0]); o[1] = sigm_new(v[1]); o[2] = sigm_new(v[2]); o[3] = sigm_new(v[3]); return o; }
; __device__ __forceinline__ f32x4 silu4_new(const f32x4 v) { return v * sigm4_new(v); }
;     __device__ __forceinline__ void operator()(const f32x4 (&acc)[2][2][4][2], const Unit& u, int wr, int wc, int fr, int fq) const {
;         const int row0 = u.pm * BM + wr * 64 + fr, c0 = u.pn * 128 + wc * 32 + 8 * fq;
;         EPI_ROWLOOP { const int r = row0 + ai * HALF + m * 16;
;             *(u32x4*)(HID + (size_t)r * ldh + c0) = pack8(silu4_new(acc[ai][0][m][0]) * acc[ai][1][m][0], silu4_new(acc[ai][0][m][1]) * acc[ai][1][m][1]); }
;     }
.LBB0_1024:
	v_mul_f32_e32 v151, 0xbfb8aa3b, v124
	v_exp_f32_e32 v151, v151
	v_mul_f32_e32 v153, 0xbfb8aa3b, v125
	v_exp_f32_e32 v155, v153
	v_and_b32_e32 v152, 0x60, v146
	v_lshlrev_b32_e32 v152, 8, v152
	v_and_or_b32 v152, v146, 31, v152
	v_add_f32_e32 v151, 1.0, v151
	v_rcp_f32_e32 v154, v151
	v_add_f32_e32 v151, 1.0, v155
	v_mul_f32_e32 v155, 0xbfb8aa3b, v126
	v_exp_f32_e32 v156, v155
	v_mul_f32_e32 v155, 0xbfb8aa3b, v127
	v_exp_f32_e32 v157, v155
	v_rcp_f32_e32 v155, v151
	v_add_f32_e32 v151, 1.0, v156
	v_rcp_f32_e32 v156, v151
	v_add_f32_e32 v151, 1.0, v157
	v_rcp_f32_e32 v157, v151
	v_mul_f32_e32 v151, 0xbfb8aa3b, v116
	v_pk_mul_f32 v[124:125], v[124:125], v[154:155]
	v_exp_f32_e32 v151, v151
	v_mul_f32_e32 v154, 0xbfb8aa3b, v117
	v_exp_f32_e32 v155, v154
	v_pk_mul_f32 v[126:127], v[126:127], v[156:157]
	v_add_f32_e32 v151, 1.0, v151
	v_rcp_f32_e32 v154, v151
	v_add_f32_e32 v151, 1.0, v155
	v_mul_f32_e32 v155, 0xbfb8aa3b, v118
	v_exp_f32_e32 v156, v155
	v_mul_f32_e32 v155, 0xbfb8aa3b, v119
	v_exp_f32_e32 v157, v155
	v_rcp_f32_e32 v155, v151
	v_add_f32_e32 v151, 1.0, v156
	v_rcp_f32_e32 v156, v151
	v_add_f32_e32 v151, 1.0, v157
	v_rcp_f32_e32 v157, v151
	v_pk_mul_f32 v[116:117], v[116:117], v[154:155]
	v_mov_b32_e32 v150, v144
	v_pk_mul_f32 v[112:113], v[112:113], v[116:117]
	v_pk_mul_f32 v[118:119], v[118:119], v[156:157]
	v_ashrrev_i32_e32 v153, 31, v152
	v_pk_mul_f32 v[120:121], v[120:121], v[124:125]
	v_pk_mul_f32 v[114:115], v[114:115], v[118:119]
	v_cvt_pk_bf16_f32 v118, v112, v113
	s_mul_i32 s100, s66, 0x160000
	s_lshl_b32 s101, s67, 16
	s_add_u32 s100, s100, s101
	s_add_u32 s100, s24, s100
	s_addc_u32 s101, s25, 0
	v_mov_b64_e32 v[112:113], s[100:101]
	s_mov_b32 s100, 0xbfb8aa3b
	s_mov_b32 s101, 0xbfb8aa3b
	s_mov_b32 s98, 1.0
	s_mov_b32 s99, 1.0
	v_pk_mul_f32 v[122:123], v[122:123], v[126:127]
	v_cvt_pk_bf16_f32 v116, v120, v121
	v_cvt_pk_bf16_f32 v119, v114, v115
	v_mad_i64_i32 v[120:121], s[42:43], v150, s63, v[112:113]
	v_lshlrev_b64 v[114:115], 1, v[152:153]
	v_cvt_pk_bf16_f32 v117, v122, v123
	v_lshl_add_u64 v[120:121], v[120:121], 0, v[114:115]
	global_store_dwordx4 v[120:121], v[116:119], off nt
	s_nop 0
	s_and_b64 vcc, exec, s[6:7]
	v_pk_mul_f32 v[116:117], v[108:109], s[100:101]
	v_pk_mul_f32 v[118:119], v[110:111], s[100:101]
	v_exp_f32_e32 v116, v116
	v_exp_f32_e32 v117, v117
	v_exp_f32_e32 v118, v118
	v_exp_f32_e32 v119, v119
	v_pk_add_f32 v[116:117], v[116:117], s[98:99]
	v_pk_add_f32 v[118:119], v[118:119], s[98:99]
	v_rcp_f32_e32 v116, v116
	v_rcp_f32_e32 v117, v117
	v_rcp_f32_e32 v118, v118
	v_rcp_f32_e32 v119, v119
	s_mov_b64 s[6:7], -1
	v_pk_mul_f32 v[108:109], v[108:109], v[116:117]
	v_pk_mul_f32 v[116:117], v[100:101], s[100:101]
	v_pk_mul_f32 v[110:111], v[110:111], v[118:119]
	v_pk_mul_f32 v[118:119], v[102:103], s[100:101]
	v_exp_f32_e32 v116, v116
	v_exp_f32_e32 v117, v117
	v_exp_f32_e32 v118, v118
	v_exp_f32_e32 v119, v119
	v_pk_add_f32 v[116:117], v[116:117], s[98:99]
	v_pk_add_f32 v[118:119], v[118:119], s[98:99]
	v_rcp_f32_e32 v116, v116
	v_rcp_f32_e32 v117, v117
	v_rcp_f32_e32 v118, v118
	v_rcp_f32_e32 v119, v119
	v_pk_mul_f32 v[106:107], v[106:107], v[110:111]
	v_pk_mul_f32 v[100:101], v[100:101], v[116:117]
	v_pk_mul_f32 v[104:105], v[104:105], v[108:109]
	v_pk_mul_f32 v[102:103], v[102:103], v[118:119]
	s_nop 0
	v_pk_mul_f32 v[102:103], v[98:99], v[102:103]
	v_pk_mul_f32 v[98:99], v[96:97], v[100:101]
	v_cvt_pk_bf16_f32 v96, v104, v105
	v_cvt_pk_bf16_f32 v97, v106, v107
	v_cvt_pk_bf16_f32 v98, v98, v99
	v_cvt_pk_bf16_f32 v99, v102, v103
	global_store_dwordx4 v[120:121], v[96:99], off offset:1024 nt
	s_nop 0
	s_nop 0
	v_pk_mul_f32 v[96:97], v[92:93], s[100:101]
	v_pk_mul_f32 v[98:99], v[94:95], s[100:101]
	v_exp_f32_e32 v96, v96
	v_exp_f32_e32 v97, v97
	v_exp_f32_e32 v98, v98
	v_exp_f32_e32 v99, v99
	v_pk_add_f32 v[96:97], v[96:97], s[98:99]
	v_pk_add_f32 v[98:99], v[98:99], s[98:99]
	v_rcp_f32_e32 v96, v96
	v_rcp_f32_e32 v97, v97
	v_rcp_f32_e32 v98, v98
	v_rcp_f32_e32 v99, v99
	v_pk_mul_f32 v[92:93], v[92:93], v[96:97]
	v_pk_mul_f32 v[96:97], v[84:85], s[100:101]
	v_pk_mul_f32 v[94:95], v[94:95], v[98:99]
	v_pk_mul_f32 v[98:99], v[86:87], s[100:101]
	v_exp_f32_e32 v96, v96
	v_exp_f32_e32 v97, v97
	v_exp_f32_e32 v98, v98
	v_exp_f32_e32 v99, v99
	v_pk_add_f32 v[96:97], v[96:97], s[98:99]
	v_pk_add_f32 v[98:99], v[98:99], s[98:99]
	v_rcp_f32_e32 v96, v96
	v_rcp_f32_e32 v97, v97
	v_rcp_f32_e32 v98, v98
	v_rcp_f32_e32 v99, v99
	v_pk_mul_f32 v[90:91], v[90:91], v[94:95]
	v_pk_mul_f32 v[84:85], v[84:85], v[96:97]
	v_pk_mul_f32 v[88:89], v[88:89], v[92:93]
	v_pk_mul_f32 v[86:87], v[86:87], v[98:99]
	s_nop 0
	v_pk_mul_f32 v[86:87], v[82:83], v[86:87]
	v_pk_mul_f32 v[82:83], v[80:81], v[84:85]
	v_cvt_pk_bf16_f32 v80, v88, v89
	v_cvt_pk_bf16_f32 v81, v90, v91
	v_cvt_pk_bf16_f32 v82, v82, v83
	v_cvt_pk_bf16_f32 v83, v86, v87
	global_store_dwordx4 v[120:121], v[80:83], off offset:2048 nt
	s_nop 0
	s_nop 0
	v_pk_mul_f32 v[80:81], v[76:77], s[100:101]
	v_pk_mul_f32 v[82:83], v[78:79], s[100:101]
	v_exp_f32_e32 v80, v80
	v_exp_f32_e32 v81, v81
	v_exp_f32_e32 v82, v82
	v_exp_f32_e32 v83, v83
	v_pk_add_f32 v[80:81], v[80:81], s[98:99]
	v_pk_add_f32 v[82:83], v[82:83], s[98:99]
	v_rcp_f32_e32 v80, v80
	v_rcp_f32_e32 v81, v81
	v_rcp_f32_e32 v82, v82
	v_rcp_f32_e32 v83, v83
	v_pk_mul_f32 v[76:77], v[76:77], v[80:81]
	v_pk_mul_f32 v[80:81], v[68:69], s[100:101]
	v_pk_mul_f32 v[78:79], v[78:79], v[82:83]
	v_pk_mul_f32 v[82:83], v[70:71], s[100:101]
	v_exp_f32_e32 v80, v80
	v_exp_f32_e32 v81, v81
	v_exp_f32_e32 v82, v82
	v_exp_f32_e32 v83, v83
	v_pk_add_f32 v[80:81], v[80:81], s[98:99]
	v_pk_add_f32 v[82:83], v[82:83], s[98:99]
; __device__ __forceinline__ u32x4 pack8(const f32x4 a, const f32x4 b) { u32x4 w; w.x = cvt_pk_bf16(a[0], a[1]); w.y = cvt_pk_bf16(a[2], a[3]); w.z = cvt_pk_bf16(b[0], b[1]); w.w = cvt_pk_bf16(b[2], b[3]); return w; }
; #define EPI_ROWLOOP _Pragma("unroll") for (int ai = 0; ai < 2; ++ai) _Pragma("unroll") for (int m = 0; m < 4; ++m)
; __device__ __forceinline__ float sigm(float x) { return __builtin_amdgcn_rcpf(1.0f + __builtin_amdgcn_exp2f(x * -1.4426950408889634f)); }
; __device__ __forceinline__ float sigm_new(float x) { return __builtin_amdgcn_rcpf(1.0f + __builtin_amdgcn_exp2f(x * -1.4426950408889634f)); }
; __device__ __forceinline__ f32x4 sigm4_new(const f32x4 v) { f32x4 o; o[0] = sigm_new(v[0]); o[1] = sigm_new(v[1]); o[2] = sigm_new(v[2]); o[3] = sigm_new(v[3]); return o; }
; __device__ __forceinline__ f32x4 silu4_new(const f32x4 v) { return v * sigm4_new(v); }
;     __device__ __forceinline__ void operator()(const f32x4 (&acc)[2][2][4][2], const Unit& u, int wr, int wc, int fr, int fq) const {
;         const int row0 = u.pm * BM + wr * 64 + fr, c0 = u.pn * 128 + wc * 32 + 8 * fq;
;         EPI_ROWLOOP { const int r = row0 + ai * HALF + m * 16;
;             *(u32x4*)(HID + (size_t)r * ldh + c0) = pack8(silu4_new(acc[ai][0][m][0]) * acc[ai][1][m][0], silu4_new(acc[ai][0][m][1]) * acc[ai][1][m][1]); }
;     }
	v_rcp_f32_e32 v80, v80
	v_rcp_f32_e32 v81, v81
	v_rcp_f32_e32 v82, v82
	v_rcp_f32_e32 v83, v83
	v_pk_mul_f32 v[74:75], v[74:75], v[78:79]
	v_pk_mul_f32 v[68:69], v[68:69], v[80:81]
	v_pk_mul_f32 v[72:73], v[72:73], v[76:77]
	v_pk_mul_f32 v[70:71], v[70:71], v[82:83]
	s_nop 0
	v_pk_mul_f32 v[70:71], v[66:67], v[70:71]
	v_pk_mul_f32 v[66:67], v[64:65], v[68:69]
	v_cvt_pk_bf16_f32 v64, v72, v73
	v_cvt_pk_bf16_f32 v65, v74, v75
	v_cvt_pk_bf16_f32 v66, v66, v67
	v_cvt_pk_bf16_f32 v67, v70, v71
	global_store_dwordx4 v[120:121], v[64:67], off offset:3072 nt
	v_add_u32_e32 v68, 0x80, v150
	s_nop 0
	v_pk_mul_f32 v[64:65], v[60:61], s[100:101]
	v_pk_mul_f32 v[66:67], v[62:63], s[100:101]
	v_exp_f32_e32 v64, v64
	v_exp_f32_e32 v65, v65
	v_exp_f32_e32 v66, v66
	v_exp_f32_e32 v67, v67
	v_pk_add_f32 v[64:65], v[64:65], s[98:99]
	v_pk_add_f32 v[66:67], v[66:67], s[98:99]
	v_rcp_f32_e32 v64, v64
	v_rcp_f32_e32 v65, v65
	v_rcp_f32_e32 v66, v66
	v_rcp_f32_e32 v67, v67
	v_pk_mul_f32 v[60:61], v[60:61], v[64:65]
	v_pk_mul_f32 v[64:65], v[52:53], s[100:101]
	v_pk_mul_f32 v[62:63], v[62:63], v[66:67]
	v_pk_mul_f32 v[66:67], v[54:55], s[100:101]
	v_exp_f32_e32 v64, v64
	v_exp_f32_e32 v65, v65
	v_exp_f32_e32 v66, v66
	v_exp_f32_e32 v67, v67
	v_pk_add_f32 v[64:65], v[64:65], s[98:99]
	v_pk_add_f32 v[66:67], v[66:67], s[98:99]
	v_rcp_f32_e32 v64, v64
	v_rcp_f32_e32 v65, v65
	v_rcp_f32_e32 v66, v66
	v_rcp_f32_e32 v67, v67
	v_pk_mul_f32 v[58:59], v[58:59], v[62:63]
	v_pk_mul_f32 v[52:53], v[52:53], v[64:65]
	v_pk_mul_f32 v[56:57], v[56:57], v[60:61]
	v_pk_mul_f32 v[54:55], v[54:55], v[66:67]
	s_nop 0
	v_pk_mul_f32 v[54:55], v[50:51], v[54:55]
	v_pk_mul_f32 v[50:51], v[48:49], v[52:53]
	v_mad_i64_i32 v[52:53], s[42:43], v68, s63, v[112:113]
	v_cvt_pk_bf16_f32 v48, v56, v57
	v_cvt_pk_bf16_f32 v49, v58, v59
	v_cvt_pk_bf16_f32 v50, v50, v51
	v_cvt_pk_bf16_f32 v51, v54, v55
	v_lshl_add_u64 v[52:53], v[52:53], 0, v[114:115]
	global_store_dwordx4 v[52:53], v[48:51], off nt
	s_nop 0
	s_nop 0
	v_pk_mul_f32 v[48:49], v[44:45], s[100:101]
	v_pk_mul_f32 v[50:51], v[46:47], s[100:101]
	v_exp_f32_e32 v48, v48
	v_exp_f32_e32 v49, v49
	v_exp_f32_e32 v50, v50
	v_exp_f32_e32 v51, v51
	v_pk_add_f32 v[48:49], v[48:49], s[98:99]
	v_pk_add_f32 v[50:51], v[50:51], s[98:99]
	v_rcp_f32_e32 v48, v48
	v_rcp_f32_e32 v49, v49
	v_rcp_f32_e32 v50, v50
	v_rcp_f32_e32 v51, v51
	v_pk_mul_f32 v[44:45], v[44:45], v[48:49]
	v_pk_mul_f32 v[48:49], v[36:37], s[100:101]
	v_pk_mul_f32 v[46:47], v[46:47], v[50:51]
	v_pk_mul_f32 v[50:51], v[38:39], s[100:101]
	v_exp_f32_e32 v48, v48
	v_exp_f32_e32 v49, v49
	v_exp_f32_e32 v50, v50
	v_exp_f32_e32 v51, v51
	v_pk_add_f32 v[48:49], v[48:49], s[98:99]
	v_pk_add_f32 v[50:51], v[50:51], s[98:99]
	v_rcp_f32_e32 v48, v48
	v_rcp_f32_e32 v49, v49
	v_rcp_f32_e32 v50, v50
	v_rcp_f32_e32 v51, v51
	v_pk_mul_f32 v[42:43], v[42:43], v[46:47]
	v_pk_mul_f32 v[36:37], v[36:37], v[48:49]
	v_pk_mul_f32 v[40:41], v[40:41], v[44:45]
	v_pk_mul_f32 v[38:39], v[38:39], v[50:51]
	s_nop 0
	v_pk_mul_f32 v[38:39], v[34:35], v[38:39]
	v_pk_mul_f32 v[34:35], v[32:33], v[36:37]
	v_cvt_pk_bf16_f32 v32, v40, v41
	v_cvt_pk_bf16_f32 v33, v42, v43
	v_cvt_pk_bf16_f32 v34, v34, v35
	v_cvt_pk_bf16_f32 v35, v38, v39
	global_store_dwordx4 v[52:53], v[32:35], off offset:1024 nt
	s_nop 0
	s_nop 0
	v_pk_mul_f32 v[32:33], v[28:29], s[100:101]
	v_pk_mul_f32 v[34:35], v[30:31], s[100:101]
	v_exp_f32_e32 v32, v32
	v_exp_f32_e32 v33, v33
	v_exp_f32_e32 v34, v34
	v_exp_f32_e32 v35, v35
	v_pk_add_f32 v[32:33], v[32:33], s[98:99]
	v_pk_add_f32 v[34:35], v[34:35], s[98:99]
	v_rcp_f32_e32 v32, v32
	v_rcp_f32_e32 v33, v33
	v_rcp_f32_e32 v34, v34
	v_rcp_f32_e32 v35, v35
	v_pk_mul_f32 v[28:29], v[28:29], v[32:33]
	v_pk_mul_f32 v[32:33], v[20:21], s[100:101]
	v_pk_mul_f32 v[30:31], v[30:31], v[34:35]
	v_pk_mul_f32 v[34:35], v[22:23], s[100:101]
	v_exp_f32_e32 v32, v32
	v_exp_f32_e32 v33, v33
	v_exp_f32_e32 v34, v34
	v_exp_f32_e32 v35, v35
	v_pk_add_f32 v[32:33], v[32:33], s[98:99]
	v_pk_add_f32 v[34:35], v[34:35], s[98:99]
	v_rcp_f32_e32 v32, v32
	v_rcp_f32_e32 v33, v33
	v_rcp_f32_e32 v34, v34
	v_rcp_f32_e32 v35, v35
	v_pk_mul_f32 v[26:27], v[26:27], v[30:31]
	v_pk_mul_f32 v[20:21], v[20:21], v[32:33]
	v_pk_mul_f32 v[24:25], v[24:25], v[28:29]
	v_pk_mul_f32 v[22:23], v[22:23], v[34:35]
	s_nop 0
	v_pk_mul_f32 v[22:23], v[18:19], v[22:23]
	v_pk_mul_f32 v[18:19], v[16:17], v[20:21]
	v_cvt_pk_bf16_f32 v16, v24, v25
	v_cvt_pk_bf16_f32 v17, v26, v27
	v_cvt_pk_bf16_f32 v18, v18, v19
	v_cvt_pk_bf16_f32 v19, v22, v23
	global_store_dwordx4 v[52:53], v[16:19], off offset:2048 nt
	s_nop 0
	s_nop 0
	v_pk_mul_f32 v[16:17], v[12:13], s[100:101]
	v_pk_mul_f32 v[18:19], v[14:15], s[100:101]
	v_exp_f32_e32 v16, v16
	v_exp_f32_e32 v17, v17
	v_exp_f32_e32 v18, v18
	v_exp_f32_e32 v19, v19
	v_pk_add_f32 v[16:17], v[16:17], s[98:99]
	v_pk_add_f32 v[18:19], v[18:19], s[98:99]
	v_rcp_f32_e32 v16, v16
	v_rcp_f32_e32 v17, v17
	v_rcp_f32_e32 v18, v18
	v_rcp_f32_e32 v19, v19
	v_pk_mul_f32 v[12:13], v[12:13], v[16:17]
	v_pk_mul_f32 v[16:17], v[4:5], s[100:101]
	v_pk_mul_f32 v[14:15], v[14:15], v[18:19]
	v_pk_mul_f32 v[18:19], v[6:7], s[100:101]
	v_exp_f32_e32 v16, v16
	v_exp_f32_e32 v17, v17
	v_exp_f32_e32 v18, v18
	v_exp_f32_e32 v19, v19
	v_pk_add_f32 v[16:17], v[16:17], s[98:99]
	v_pk_add_f32 v[18:19], v[18:19], s[98:99]
	v_rcp_f32_e32 v16, v16
	v_rcp_f32_e32 v17, v17
	v_rcp_f32_e32 v18, v18
	v_rcp_f32_e32 v19, v19
	v_pk_mul_f32 v[10:11], v[10:11], v[14:15]
	v_pk_mul_f32 v[4:5], v[4:5], v[16:17]
	v_pk_mul_f32 v[8:9], v[8:9], v[12:13]
	v_pk_mul_f32 v[6:7], v[6:7], v[18:19]
	s_nop 0
	v_pk_mul_f32 v[6:7], v[2:3], v[6:7]
	v_pk_mul_f32 v[2:3], v[0:1], v[4:5]
	v_cvt_pk_bf16_f32 v0, v8, v9
	v_cvt_pk_bf16_f32 v1, v10, v11
	v_cvt_pk_bf16_f32 v2, v2, v3
	v_cvt_pk_bf16_f32 v3, v6, v7
	global_store_dwordx4 v[52:53], v[0:3], off offset:3072 nt
	s_cbranch_vccnz .LBB0_1012
	s_andn2_b64 vcc, exec, s[14:15]
	s_cbranch_vccnz .LBB0_1011
	s_barrier
	s_branch .LBB0_1011
